# first-barrier census loads batched; layer-0 second-norm K-slice partial loads batched (8 in flight)
# baseline (speedup 1.0000x reference)
.LBB0_156:
	v_readlane_b32 s4, v253, 7
	v_readlane_b32 s5, v253, 8
	v_readlane_b32 s6, v254, 39
	s_waitcnt lgkmcnt(0)
	s_nop 2
	global_load_dword v0, v1, s[4:5] sc1
	v_readlane_b32 s4, v253, 9
	v_readlane_b32 s5, v253, 10
	s_nop 4
	global_load_dword v2, v1, s[4:5] sc1
	v_readlane_b32 s4, v253, 11
	v_readlane_b32 s5, v253, 12
	s_nop 4
	global_load_dword v3, v1, s[4:5] sc1
	v_readlane_b32 s4, v253, 13
	v_readlane_b32 s5, v253, 14
	s_nop 4
	global_load_dword v4, v1, s[4:5] sc1
	v_readlane_b32 s4, v253, 15
	v_readlane_b32 s5, v253, 16
	s_nop 4
	global_load_dword v5, v1, s[4:5] sc1
	v_readlane_b32 s4, v253, 17
	v_readlane_b32 s5, v253, 18
	s_nop 4
	global_load_dword v6, v1, s[4:5] sc1
	v_readlane_b32 s4, v253, 19
	v_readlane_b32 s5, v253, 20
	s_nop 4
	global_load_dword v7, v1, s[4:5] sc1
	v_readlane_b32 s4, v253, 21
	v_readlane_b32 s5, v253, 22
	s_nop 4
	global_load_dword v8, v1, s[4:5] sc1
	v_readlane_b32 s4, v253, 23
	v_readlane_b32 s5, v253, 24
	s_nop 4
	global_load_dword v9, v1, s[4:5] sc1
	v_readlane_b32 s4, v253, 25
	v_readlane_b32 s5, v253, 26
	s_nop 4
	global_load_dword v10, v1, s[4:5] sc1
	v_readlane_b32 s4, v253, 27
	v_readlane_b32 s5, v253, 28
	s_nop 4
	global_load_dword v11, v1, s[4:5] sc1
	v_readlane_b32 s4, v253, 29
	v_readlane_b32 s5, v253, 30
	s_nop 4
	global_load_dword v12, v1, s[4:5] sc1
	v_readlane_b32 s4, v253, 31
	v_readlane_b32 s5, v253, 32
	s_nop 4
	global_load_dword v13, v1, s[4:5] sc1
	v_readlane_b32 s4, v253, 33
	v_readlane_b32 s5, v253, 34
	s_nop 4
	global_load_dword v14, v1, s[4:5] sc1
	v_readlane_b32 s4, v253, 35
	v_readlane_b32 s5, v253, 36
	s_nop 4
	global_load_dword v15, v1, s[4:5] sc1
	v_readlane_b32 s4, v253, 37
	v_readlane_b32 s5, v253, 38
	s_nop 4
	global_load_dword v16, v1, s[4:5] sc1
	s_mov_b64 s[4:5], -1
	s_waitcnt vmcnt(0)
	v_add_u32_e32 v17, v2, v0
	v_add_u32_e32 v17, v17, v3
	v_add_u32_e32 v17, v17, v4
	v_add_u32_e32 v17, v17, v5
	v_add_u32_e32 v17, v17, v6
	v_add_u32_e32 v17, v17, v7
	v_add_u32_e32 v17, v17, v8
	v_add_u32_e32 v17, v17, v9
	v_add_u32_e32 v17, v17, v10
	v_add_u32_e32 v17, v17, v11
	v_add_u32_e32 v17, v17, v12
	v_add_u32_e32 v17, v17, v13
	v_add_u32_e32 v17, v17, v14
	v_add_u32_e32 v17, v17, v15
	v_add_u32_e32 v17, v17, v16
	v_cmp_eq_u32_e32 vcc, s6, v17
	s_mov_b64 s[6:7], -1
	s_cbranch_vccnz .LBB0_155
	s_and_b32 s4, s10, 0xff
	s_cmp_eq_u32 s4, 0
	s_mov_b64 s[4:5], -1
	s_mov_b64 s[8:9], -1
	s_sleep 1
	s_cbranch_scc1 .LBB0_160
	s_and_b64 vcc, exec, s[8:9]
	s_cbranch_vccz .LBB0_155

.LBB0_958:
	v_lshl_add_u64 v[28:29], v[26:27], 0, s[10:11]
	v_add_co_u32_e32 v32, vcc, s22, v28
	s_nop 1
	v_addc_co_u32_e32 v33, vcc, 0, v29, vcc
	global_load_dwordx2 v[152:153], v[32:33], off
	s_mov_b32 s3, 0x7c20000
	v_add_co_u32_e32 v32, vcc, s3, v28
	s_nop 1
	v_addc_co_u32_e32 v33, vcc, 0, v29, vcc
	global_load_dwordx2 v[154:155], v[32:33], off
	s_mov_b32 s3, 0x7c40000
	v_add_co_u32_e32 v32, vcc, s3, v28
	s_nop 1
	v_addc_co_u32_e32 v33, vcc, 0, v29, vcc
	global_load_dwordx2 v[156:157], v[32:33], off
	s_mov_b32 s3, 0x7c60000
	v_add_co_u32_e32 v32, vcc, s3, v28
	s_nop 1
	v_addc_co_u32_e32 v33, vcc, 0, v29, vcc
	global_load_dwordx2 v[158:159], v[32:33], off
	s_mov_b32 s3, 0x7e00000
	v_add_co_u32_e32 v32, vcc, s3, v28
	s_nop 1
	v_addc_co_u32_e32 v33, vcc, 0, v29, vcc
	global_load_dwordx2 v[160:161], v[32:33], off
	s_mov_b32 s3, 0x7e20000
	v_add_co_u32_e32 v32, vcc, s3, v28
	s_nop 1
	v_addc_co_u32_e32 v33, vcc, 0, v29, vcc
	global_load_dwordx2 v[162:163], v[32:33], off
	s_mov_b32 s3, 0x7e40000
	v_add_co_u32_e32 v32, vcc, s3, v28
	s_nop 1
	v_addc_co_u32_e32 v33, vcc, 0, v29, vcc
	global_load_dwordx2 v[164:165], v[32:33], off
	s_mov_b32 s3, 0x7e60000
	v_add_co_u32_e32 v32, vcc, s3, v28
	s_nop 1
	v_addc_co_u32_e32 v33, vcc, 0, v29, vcc
	global_load_dwordx2 v[166:167], v[32:33], off
	s_add_u32 s10, s10, 0x400000
	s_addc_u32 s11, s11, 0
	s_cmp_lg_u32 s10, 0x1000000
	s_waitcnt vmcnt(0)
	v_lshlrev_b32_e32 v34, 16, v152
	v_and_b32_e32 v35, 0xffff0000, v152
	v_lshlrev_b32_e32 v32, 16, v153
	v_and_b32_e32 v33, 0xffff0000, v153
	v_pk_add_f32 v[16:17], v[16:17], v[32:33]
	v_pk_add_f32 v[14:15], v[14:15], v[34:35]
	v_lshlrev_b32_e32 v34, 16, v154
	v_and_b32_e32 v35, 0xffff0000, v154
	v_lshlrev_b32_e32 v32, 16, v155
	v_and_b32_e32 v33, 0xffff0000, v155
	v_pk_add_f32 v[12:13], v[12:13], v[32:33]
	v_pk_add_f32 v[10:11], v[10:11], v[34:35]
	v_lshlrev_b32_e32 v34, 16, v156
	v_and_b32_e32 v35, 0xffff0000, v156
	v_lshlrev_b32_e32 v32, 16, v157
	v_and_b32_e32 v33, 0xffff0000, v157
	v_pk_add_f32 v[4:5], v[4:5], v[32:33]
	v_pk_add_f32 v[2:3], v[2:3], v[34:35]
	v_lshlrev_b32_e32 v34, 16, v158
	v_and_b32_e32 v35, 0xffff0000, v158
	v_lshlrev_b32_e32 v32, 16, v159
	v_and_b32_e32 v33, 0xffff0000, v159
	v_pk_add_f32 v[8:9], v[8:9], v[32:33]
	v_pk_add_f32 v[6:7], v[6:7], v[34:35]
	v_lshlrev_b32_e32 v34, 16, v160
	v_and_b32_e32 v35, 0xffff0000, v160
	v_lshlrev_b32_e32 v32, 16, v161
	v_and_b32_e32 v33, 0xffff0000, v161
	v_pk_add_f32 v[16:17], v[16:17], v[32:33]
	v_pk_add_f32 v[14:15], v[14:15], v[34:35]
	v_lshlrev_b32_e32 v34, 16, v162
	v_and_b32_e32 v35, 0xffff0000, v162
	v_lshlrev_b32_e32 v32, 16, v163
	v_and_b32_e32 v33, 0xffff0000, v163
	v_pk_add_f32 v[12:13], v[12:13], v[32:33]
	v_pk_add_f32 v[10:11], v[10:11], v[34:35]
	v_lshlrev_b32_e32 v34, 16, v164
	v_and_b32_e32 v35, 0xffff0000, v164
	v_lshlrev_b32_e32 v32, 16, v165
	v_and_b32_e32 v33, 0xffff0000, v165
	v_pk_add_f32 v[4:5], v[4:5], v[32:33]
	v_pk_add_f32 v[2:3], v[2:3], v[34:35]
	v_lshlrev_b32_e32 v34, 16, v166
	v_and_b32_e32 v35, 0xffff0000, v166
	v_lshlrev_b32_e32 v32, 16, v167
	v_and_b32_e32 v33, 0xffff0000, v167
	v_pk_add_f32 v[8:9], v[8:9], v[32:33]
	v_pk_add_f32 v[6:7], v[6:7], v[34:35]
	s_cbranch_scc1 .LBB0_958
	s_mov_b32 s10, 27
	s_ashr_i32 s11, s10, 31
	s_lshl_b64 s[10:11], s[10:11], 3
	s_add_u32 s10, s0, s10
	s_addc_u32 s11, s1, s11
	s_load_dwordx2 s[10:11], s[10:11], 0x0
	s_lshl_b64 s[8:9], s[8:9], 20
	s_waitcnt lgkmcnt(0)
	s_add_u32 s3, s10, s8
	s_addc_u32 s8, s11, s9
	s_lshl_b64 s[6:7], s[6:7], 12
	s_add_u32 s6, s3, s6
	s_addc_u32 s7, s8, s7
	v_lshl_add_u64 v[26:27], s[6:7], 0, v[0:1]
	s_mov_b64 s[6:7], 0x3600000
	s_mov_b32 s3, 0x3600000
	v_lshl_add_u64 v[28:29], v[26:27], 0, s[6:7]
	v_add_co_u32_e32 v26, vcc, s3, v26
	s_nop 1
	v_addc_co_u32_e32 v27, vcc, 0, v27, vcc
	global_store_dwordx4 v[26:27], v[14:17], off
	global_store_dwordx4 v[28:29], v[10:13], off offset:1024
	global_store_dwordx4 v[28:29], v[2:5], off offset:2048
	global_store_dwordx4 v[28:29], v[6:9], off offset:3072
	s_branch .LBB0_951
